# code placement: 28 bytes of padding at the attention phase entry so the attention loop lands on the byte offset that probed fastest
# speedup vs baseline: 1.0045x; 1.0011x over previous
; #define LAS __attribute__((address_space(3)))
; __device__ __forceinline__ void attn_unit(const Ctx& C, int qrow0, int krow0, int h, int NT, int ntw) {
;     const bf16_t* Q = (const bf16_t*)(C.ws + WS_ZRX); const bf16_t* KN = (const bf16_t*)(C.ws + WS_ZRG); const bf16_t* KRp = (const bf16_t*)(C.ws + WS_KR);
;     const bf16_t* VT = (const bf16_t*)(C.ws + WS_AB); bf16_t* O = (bf16_t*)(C.ws + WS_ZA);
;     int tid_ = threadIdx.x; asm volatile("" : "+v"(tid_));
;     const int tid = tid_, lane = tid & 63, wid = __builtin_amdgcn_readfirstlane(tid >> 6), r32 = lane & 31, hi = lane >> 5;
;     LAS unsigned char* lds = C.lds;
;     bf16x8 qr[6];
;     if (ntw > 0) {
; #pragma unroll
;         for (int ds = 0; ds < 6; ++ds) qr[ds] = *(const bf16x8*)(Q + (size_t)(qrow0 + wid * 32 + r32) * 768 + h * 96 + ds * 16 + hi * 8);
;     } else {
; #pragma unroll
;         for (int ds = 0; ds < 6; ++ds) qr[ds] = (bf16x8){0, 0, 0, 0, 0, 0, 0, 0};
;     }
;     const bf16_t* ksrc = KN + (size_t)(krow0 + (tid >> 3)) * 512 + h * 64 + (tid & 7) * 8;
;     const bf16_t* rsrc = KRp + (size_t)(krow0 + ((tid & 255) >> 2)) * 32 + (tid & 3) * 8;
;     const bf16_t* vsrc = VT + (size_t)(h * 64 + (tid >> 3)) * KVROWS + krow0 + (tid & 7) * 8;
;     const int kdst = (tid >> 3) * KT_STRIDE + (tid & 7) * 16, rdst = ((tid & 255) >> 2) * KT_STRIDE + 128 + (tid & 3) * 16;
;     const int vdst = AT_V0 + (tid >> 3) * VT_STRIDE + (((tid & 7) >> 1) * 16 + 4 * (tid & 1)) * 2;
;     u32x4 kA, rA, vA, kB, rB, vB;
;     ...
;     f32x16 o0 = {}, o1 = {}, negm = {}; float mrun = 0.f, lrun = 0.f;
;     asm volatile("" : "+v"(negm));
;     if (wid >= 4) __builtin_amdgcn_s_setprio(1);
;     const LAS unsigned char* Kl = lds + AT_K0 + r32 * KT_STRIDE + hi * 16; const LAS unsigned char* Vl = lds + AT_V0 + r32 * VT_STRIDE + hi * 16;
; __device__ __forceinline__ void p9_attn(const Ctx& C) {
;     for (int k = C.vcu; k < 576; k += C.G) {
;         if (k < 512) { const int bh = k >> 5, j = k & 31, b = bh >> 3, h = bh & 7;
; #pragma unroll 1
;             for (int e = 0; e < 2; ++e) { const int qb = e == 0 ? 63 - j : j; attn_unit(C, b * SEQ + 256 * qb, b * SEQ, h, 4 * qb + 4, 4 * qb + (C.wave >> 1) + 1); } }
;         else { const int s = k - 512, bs = s >> 3, h = s & 7; attn_unit(C, MP + bs * 64, MP + bs * SKV, h, 17, C.wave < 2 ? 17 : 0); }
.LBB0_1101:
	s_or_b64 exec, exec, s[0:1]
	s_nop 0
	s_nop 0
	s_nop 0
	s_nop 0
	s_nop 0
	s_nop 0
	s_nop 0
	s_cmpk_gt_i32 s2, 0x23f
	s_waitcnt lgkmcnt(0)
	s_barrier
	s_cbranch_scc1 .LBB0_1214
	v_readlane_b32 s4, v255, 0
	s_cmpk_lt_u32 s4, 0x80
	s_cselect_b64 s[0:1], -1, 0
	v_cndmask_b32_e64 v2, 0, 1, s[0:1]
	s_and_b64 s[0:1], s[0:1], exec
	s_cselect_b32 s14, 17, 0
	s_lshr_b32 s15, s4, 7
	v_cmp_ne_u32_e64 s[4:5], 1, v2
	v_mbcnt_lo_u32_b32 v2, -1, 0
	s_mov_b32 s11, 0
	s_add_i32 s33, s2, 0xfffffe00
	s_lshl_b32 s35, s2, 6
	s_lshl_b32 s40, s3, 6
	s_movk_i32 s41, 0x600
	v_mov_b32_e32 v3, 0
	s_movk_i32 s64, 0xff
	s_movk_i32 s65, 0x100
	s_mov_b32 s66, 0x14400
	s_movk_i32 s67, 0xd0
	s_movk_i32 s68, 0x60
	s_movk_i32 s69, 0x90
	s_mov_b32 s70, 0x41000000
	s_mov_b64 s[12:13], 0x2000
	s_mov_b64 s[38:39], 0x100
	s_mov_b64 s[42:43], 0x20000
	v_mbcnt_hi_u32_b32 v141, -1, v2
	s_mov_b32 s71, s2
	s_branch .LBB0_1104
